# attention: skip the window-mask block for the three middle local tiles (|q-k|<=127 always)
# speedup vs baseline: 1.0168x; 1.0168x over previous
.Lapf0_d:
	s_waitcnt lgkmcnt(0)
	s_barrier
	ds_read_b128 v[28:31], v77
	ds_read_b128 v[32:35], v77 offset:64
	s_waitcnt lgkmcnt(1)
	v_mfma_f32_16x16x32_bf16 v[28:31], v[4:7], v[28:31], 0
	s_and_b64 s[6:7], s[0:1], s[12:13]
	s_andn2_b64 vcc, exec, s[6:7]
	s_add_i32 s6, s22, -1
	s_cmp_lt_u32 s6, 3
	s_cselect_b64 s[6:7], exec, 0
	s_or_b64 vcc, vcc, s[6:7]
	s_waitcnt lgkmcnt(0)
	v_mfma_f32_16x16x32_bf16 v[28:31], v[8:11], v[32:35], v[28:31]
	ds_read_b128 v[32:35], v77 offset:2304
	ds_read_b128 v[36:39], v77 offset:2368
	s_waitcnt lgkmcnt(1)
	v_mfma_f32_16x16x32_bf16 v[32:35], v[4:7], v[32:35], 0
	s_waitcnt lgkmcnt(0)
	v_mfma_f32_16x16x32_bf16 v[32:35], v[8:11], v[36:39], v[32:35]
	ds_read_b128 v[36:39], v77 offset:4608
	ds_read_b128 v[40:43], v77 offset:4672
	s_waitcnt lgkmcnt(1)
	v_mfma_f32_16x16x32_bf16 v[36:39], v[4:7], v[36:39], 0
	s_waitcnt lgkmcnt(0)
	v_mfma_f32_16x16x32_bf16 v[36:39], v[8:11], v[40:43], v[36:39]
	ds_read_b128 v[40:43], v77 offset:6912
	ds_read_b128 v[56:59], v77 offset:6976
	s_waitcnt lgkmcnt(1)
	v_mfma_f32_16x16x32_bf16 v[40:43], v[4:7], v[40:43], 0
	s_waitcnt lgkmcnt(0)
	v_mfma_f32_16x16x32_bf16 v[40:43], v[8:11], v[56:59], v[40:43]
	s_cbranch_vccnz .LBB0_870
	v_add_u32_e32 v56, s26, v45
	v_sub_u32_e32 v57, v69, v56
	v_sub_u32_e32 v58, 0, v57
	v_max_i32_e32 v58, v57, v58
	s_movk_i32 s6, 0x80
	v_cmp_lt_u32_e32 vcc, s6, v58
	v_add_u32_e32 v58, 1, v57
	v_not_b32_e32 v59, v57
	v_max_i32_e32 v58, v58, v59
	v_cndmask_b32_e32 v28, v28, v118, vcc
	v_cmp_gt_u32_e32 vcc, s74, v58
	v_add_u32_e32 v58, 2, v57
	v_sub_u32_e32 v59, -2, v57
	v_max_i32_e32 v58, v58, v59
	v_cndmask_b32_e32 v29, v118, v29, vcc
	v_cmp_gt_u32_e32 vcc, s74, v58
	v_add_u32_e32 v58, 3, v57
	v_sub_u32_e32 v57, -3, v57
	v_max_i32_e32 v57, v58, v57
	v_cndmask_b32_e32 v30, v118, v30, vcc
	v_cmp_gt_u32_e32 vcc, s74, v57
	v_sub_u32_e32 v57, v70, v56
	v_sub_u32_e32 v58, 0, v57
	v_max_i32_e32 v58, v57, v58
	v_cndmask_b32_e32 v31, v118, v31, vcc
	v_cmp_gt_u32_e32 vcc, s74, v58
	v_add_u32_e32 v58, 1, v57
	v_not_b32_e32 v59, v57
	v_max_i32_e32 v58, v58, v59
	v_cndmask_b32_e32 v32, v118, v32, vcc
	v_cmp_gt_u32_e32 vcc, s74, v58
	v_add_u32_e32 v58, 2, v57
	v_sub_u32_e32 v59, -2, v57
	v_max_i32_e32 v58, v58, v59
	v_cndmask_b32_e32 v33, v118, v33, vcc
	v_cmp_gt_u32_e32 vcc, s74, v58
	v_add_u32_e32 v58, 3, v57
	v_sub_u32_e32 v57, -3, v57
	v_max_i32_e32 v57, v58, v57
	v_cndmask_b32_e32 v34, v118, v34, vcc
	v_cmp_gt_u32_e32 vcc, s74, v57
	v_sub_u32_e32 v57, v71, v56
	v_sub_u32_e32 v58, 0, v57
	v_max_i32_e32 v58, v57, v58
	v_cndmask_b32_e32 v35, v118, v35, vcc
	v_cmp_gt_u32_e32 vcc, s74, v58
	v_add_u32_e32 v58, 1, v57
	v_not_b32_e32 v59, v57
	v_max_i32_e32 v58, v58, v59
	v_cndmask_b32_e32 v36, v118, v36, vcc
	v_cmp_gt_u32_e32 vcc, s74, v58
	v_add_u32_e32 v58, 2, v57
	v_sub_u32_e32 v59, -2, v57
	v_max_i32_e32 v58, v58, v59
	v_cndmask_b32_e32 v37, v118, v37, vcc
	v_cmp_gt_u32_e32 vcc, s74, v58
	v_add_u32_e32 v58, 3, v57
	v_sub_u32_e32 v57, -3, v57
	v_max_i32_e32 v57, v58, v57
	v_sub_u32_e32 v56, v72, v56
	v_cndmask_b32_e32 v38, v118, v38, vcc
	v_cmp_gt_u32_e32 vcc, s74, v57
	v_sub_u32_e32 v57, 0, v56
	v_max_i32_e32 v57, v56, v57
	v_cndmask_b32_e32 v39, v118, v39, vcc
	v_cmp_gt_u32_e32 vcc, s74, v57
	v_add_u32_e32 v57, 1, v56
	v_not_b32_e32 v58, v56
	v_max_i32_e32 v57, v57, v58
	v_cndmask_b32_e32 v40, v118, v40, vcc
	v_cmp_gt_u32_e32 vcc, s74, v57
	v_add_u32_e32 v57, 2, v56
	v_sub_u32_e32 v58, -2, v56
	v_max_i32_e32 v57, v57, v58
	v_cndmask_b32_e32 v41, v118, v41, vcc
	v_cmp_gt_u32_e32 vcc, s74, v57
	v_add_u32_e32 v57, 3, v56
	v_sub_u32_e32 v56, -3, v56
	v_max_i32_e32 v56, v57, v56
	v_cndmask_b32_e32 v42, v118, v42, vcc
	v_cmp_gt_u32_e32 vcc, s74, v56
	s_nop 1
	v_cndmask_b32_e32 v43, v118, v43, vcc
	s_branch .LBB0_870

.Lapf1_d:
	s_waitcnt lgkmcnt(0)
	s_barrier
	ds_read_b128 v[28:31], v77
	ds_read_b128 v[32:35], v77 offset:64
	s_waitcnt lgkmcnt(1)
	v_mfma_f32_16x16x32_bf16 v[28:31], v[4:7], v[28:31], 0
	s_and_b64 s[6:7], s[0:1], s[12:13]
	s_andn2_b64 vcc, exec, s[6:7]
	s_add_i32 s6, s21, -1
	s_cmp_lt_u32 s6, 3
	s_cselect_b64 s[6:7], exec, 0
	s_or_b64 vcc, vcc, s[6:7]
	s_waitcnt lgkmcnt(0)
	v_mfma_f32_16x16x32_bf16 v[28:31], v[8:11], v[32:35], v[28:31]
	ds_read_b128 v[32:35], v77 offset:2304
	ds_read_b128 v[36:39], v77 offset:2368
	s_waitcnt lgkmcnt(1)
	v_mfma_f32_16x16x32_bf16 v[32:35], v[4:7], v[32:35], 0
	s_waitcnt lgkmcnt(0)
	v_mfma_f32_16x16x32_bf16 v[32:35], v[8:11], v[36:39], v[32:35]
	ds_read_b128 v[36:39], v77 offset:4608
	ds_read_b128 v[40:43], v77 offset:4672
	s_waitcnt lgkmcnt(1)
	v_mfma_f32_16x16x32_bf16 v[36:39], v[4:7], v[36:39], 0
	s_waitcnt lgkmcnt(0)
	v_mfma_f32_16x16x32_bf16 v[36:39], v[8:11], v[40:43], v[36:39]
	ds_read_b128 v[40:43], v77 offset:6912
	ds_read_b128 v[56:59], v77 offset:6976
	s_waitcnt lgkmcnt(1)
	v_mfma_f32_16x16x32_bf16 v[40:43], v[4:7], v[40:43], 0
	s_waitcnt lgkmcnt(0)
	v_mfma_f32_16x16x32_bf16 v[40:43], v[8:11], v[56:59], v[40:43]
	s_cbranch_vccnz .LBB0_2356
	v_add_u32_e32 v56, s25, v45
	v_sub_u32_e32 v57, v69, v56
	v_sub_u32_e32 v58, 0, v57
	v_max_i32_e32 v58, v57, v58
	s_movk_i32 s6, 0x80
	v_cmp_lt_u32_e32 vcc, s6, v58
	v_add_u32_e32 v58, 1, v57
	v_not_b32_e32 v59, v57
	v_max_i32_e32 v58, v58, v59
	v_cndmask_b32_e32 v28, v28, v118, vcc
	v_cmp_gt_u32_e32 vcc, s70, v58
	v_add_u32_e32 v58, 2, v57
	v_sub_u32_e32 v59, -2, v57
	v_max_i32_e32 v58, v58, v59
	v_cndmask_b32_e32 v29, v118, v29, vcc
	v_cmp_gt_u32_e32 vcc, s70, v58
	v_add_u32_e32 v58, 3, v57
	v_sub_u32_e32 v57, -3, v57
	v_max_i32_e32 v57, v58, v57
	v_cndmask_b32_e32 v30, v118, v30, vcc
	v_cmp_gt_u32_e32 vcc, s70, v57
	v_sub_u32_e32 v57, v70, v56
	v_sub_u32_e32 v58, 0, v57
	v_max_i32_e32 v58, v57, v58
	v_cndmask_b32_e32 v31, v118, v31, vcc
	v_cmp_gt_u32_e32 vcc, s70, v58
	v_add_u32_e32 v58, 1, v57
	v_not_b32_e32 v59, v57
	v_max_i32_e32 v58, v58, v59
	v_cndmask_b32_e32 v32, v118, v32, vcc
	v_cmp_gt_u32_e32 vcc, s70, v58
	v_add_u32_e32 v58, 2, v57
	v_sub_u32_e32 v59, -2, v57
	v_max_i32_e32 v58, v58, v59
	v_cndmask_b32_e32 v33, v118, v33, vcc
	v_cmp_gt_u32_e32 vcc, s70, v58
	v_add_u32_e32 v58, 3, v57
	v_sub_u32_e32 v57, -3, v57
	v_max_i32_e32 v57, v58, v57
	v_cndmask_b32_e32 v34, v118, v34, vcc
	v_cmp_gt_u32_e32 vcc, s70, v57
	v_sub_u32_e32 v57, v71, v56
	v_sub_u32_e32 v58, 0, v57
	v_max_i32_e32 v58, v57, v58
	v_cndmask_b32_e32 v35, v118, v35, vcc
	v_cmp_gt_u32_e32 vcc, s70, v58
	v_add_u32_e32 v58, 1, v57
	v_not_b32_e32 v59, v57
	v_max_i32_e32 v58, v58, v59
	v_cndmask_b32_e32 v36, v118, v36, vcc
	v_cmp_gt_u32_e32 vcc, s70, v58
	v_add_u32_e32 v58, 2, v57
	v_sub_u32_e32 v59, -2, v57
	v_max_i32_e32 v58, v58, v59
	v_cndmask_b32_e32 v37, v118, v37, vcc
	v_cmp_gt_u32_e32 vcc, s70, v58
	v_add_u32_e32 v58, 3, v57
	v_sub_u32_e32 v57, -3, v57
	v_max_i32_e32 v57, v58, v57
	v_sub_u32_e32 v56, v72, v56
	v_cndmask_b32_e32 v38, v118, v38, vcc
	v_cmp_gt_u32_e32 vcc, s70, v57
	v_sub_u32_e32 v57, 0, v56
	v_max_i32_e32 v57, v56, v57
	v_cndmask_b32_e32 v39, v118, v39, vcc
	v_cmp_gt_u32_e32 vcc, s70, v57
	v_add_u32_e32 v57, 1, v56
	v_not_b32_e32 v58, v56
	v_max_i32_e32 v57, v57, v58
	v_cndmask_b32_e32 v40, v118, v40, vcc
	v_cmp_gt_u32_e32 vcc, s70, v57
	v_add_u32_e32 v57, 2, v56
	v_sub_u32_e32 v58, -2, v56
	v_max_i32_e32 v57, v57, v58
	v_cndmask_b32_e32 v41, v118, v41, vcc
	v_cmp_gt_u32_e32 vcc, s70, v57
	v_add_u32_e32 v57, 3, v56
	v_sub_u32_e32 v56, -3, v56
	v_max_i32_e32 v56, v57, v56
	v_cndmask_b32_e32 v42, v118, v42, vcc
	v_cmp_gt_u32_e32 vcc, s70, v56
	s_nop 1
	v_cndmask_b32_e32 v43, v118, v43, vcc
	s_branch .LBB0_2356
